# GEMM phases: static s_setprio 1 for waves 0-3 instead (P1, P3/P4), reset to 0 for LRU/attention
# baseline (speedup 1.0000x reference)
.LBB0_142:
	v_readfirstlane_b32 s32, v254
	s_cmpk_lt_u32 s32, 0x100
	s_cbranch_scc0 .Lgprio_1
	s_setprio 1
